# prep token-shift: last 2 of 8 passes of blocks 0-191 handed to the 48 idle workgroups (virtual block ids), gridDim==256 guard
# speedup vs baseline: 1.0039x; 1.0014x over previous
.LBB0_541:
	s_andn2_b64 vcc, exec, s[0:1]
	s_cbranch_vccnz .LBB0_729
	s_cmp_gt_i32 s96, 0
	s_mov_b64 s[0:1], -1
	s_cbranch_scc0 .LBB0_715
	s_mov_b32 s98, s82
	s_movk_i32 s99, 14
	s_cmpk_lg_i32 s71, 0x100
	s_cbranch_scc1 .Lpa_go
	s_cmpk_lt_u32 s82, 0xc0
	s_cselect_b32 s99, 10, 14
	s_cmpk_lt_u32 s82, 0xd0
	s_cbranch_scc1 .Lpa_go
	s_sub_u32 s98, s82, 0xd0
	s_lshl_b32 s98, s98, 2
.Lpa_go:
	v_lshl_add_u32 v81, s98, 9, v198
	s_mov_b32 s0, 0x1a000
	v_cmp_gt_i32_e32 vcc, s0, v81
	s_and_saveexec_b64 s[4:5], vcc
	s_cbranch_execz .LBB0_628
	v_readlane_b32 s0, v254, 31
	v_readlane_b32 s1, v254, 32
	s_mov_b32 s6, 0x4ec4ec4f
	s_load_dwordx2 s[0:1], s[0:1], 0x18
	v_mul_hi_i32 v0, v81, s6
	v_lshrrev_b32_e32 v1, 31, v0
	v_ashrrev_i32_e32 v0, 7, v0
	s_waitcnt vmcnt(0)
	v_add_u32_e32 v8, v0, v1
	v_readlane_b32 s8, v254, 35
	v_mul_i32_i24_e32 v0, 0x1a0, v8
	s_mul_i32 s3, s8, 0x6800
	v_sub_u32_e32 v9, v81, v0
	s_mul_hi_i32 s2, s8, 0x6800
	s_waitcnt lgkmcnt(0)
	s_add_u32 s0, s0, s3
	v_lshlrev_b32_e32 v30, 3, v9
	s_addc_u32 s1, s1, s2
	v_ashrrev_i32_e32 v31, 31, v30
	v_lshl_add_u64 v[14:15], v[30:31], 2, s[0:1]
	s_mov_b64 s[0:1], 0x3400
	global_load_dwordx4 v[0:3], v[14:15], off offset:16
	global_load_dwordx4 v[4:7], v[14:15], off
	v_lshl_add_u64 v[18:19], v[14:15], 0, s[0:1]
	v_add_co_u32_e32 v14, vcc, 0x3000, v14
	v_and_b32_e32 v22, 0xffffff80, v9
	s_nop 0
	v_addc_co_u32_e32 v15, vcc, 0, v15, vcc
	global_load_dwordx4 v[14:17], v[14:15], off offset:1024
	s_nop 0
	global_load_dwordx4 v[18:21], v[18:19], off offset:16
	s_movk_i32 s0, 0x80
	v_cmp_eq_u32_e64 s[40:41], s0, v22
	v_mov_b32_e32 v22, 0
	v_mov_b32_e32 v23, 0
	v_mov_b32_e32 v24, 0
	v_mov_b32_e32 v25, 0
	v_mov_b32_e32 v26, 0
	v_mov_b32_e32 v27, 0
	v_mov_b32_e32 v28, 0
	v_mov_b32_e32 v29, 0
	v_readlane_b32 s9, v254, 36
	s_and_saveexec_b64 s[0:1], s[40:41]
	s_cbranch_execz .LBB0_546
	v_readlane_b32 s2, v254, 31
	v_readlane_b32 s3, v254, 32
	s_load_dwordx2 s[2:3], s[2:3], 0x40
	s_ashr_i32 s9, s8, 31
	s_lshl_b64 s[6:7], s[8:9], 12
	s_waitcnt lgkmcnt(0)
	s_add_u32 s2, s2, s6
	s_addc_u32 s3, s3, s7
	v_lshl_add_u64 v[26:27], v[30:31], 2, s[2:3]
	global_load_dwordx4 v[22:25], v[26:27], off offset:-4096
	s_nop 0
	global_load_dwordx4 v[26:29], v[26:27], off offset:-4080
.LBB0_546:
	s_or_b64 exec, exec, s[0:1]
	v_ashrrev_i32_e32 v32, 7, v9
	s_movk_i32 s0, 0x17f
	v_ashrrev_i32_e32 v33, 31, v32
	v_cmp_lt_i32_e64 s[42:43], s0, v9
	s_movk_i32 s0, 0x190
	v_lshlrev_b64 v[32:33], 25, v[32:33]
	v_and_b32_e32 v34, 56, v30
	v_cmp_gt_u32_e64 s[44:45], s0, v9
	v_lshl_add_u64 v[32:33], s[38:39], 0, v[32:33]
	v_lshlrev_b32_e32 v34, 1, v34
	v_mov_b32_e32 v35, v195
	v_and_b32_e32 v9, 7, v9
	v_lshlrev_b32_e32 v8, 2, v8
	v_lshl_add_u64 v[32:33], v[32:33], 0, v[34:35]
	s_mov_b64 s[0:1], 0x1202b400
	v_cmp_eq_u32_e64 s[46:47], 0, v9
	v_add_u32_e32 v9, 0xfffffc00, v30
	v_lshl_add_u64 v[78:79], v[32:33], 0, s[0:1]
	v_lshrrev_b32_e32 v111, 6, v9
	v_and_b32_e32 v80, 0x7fc, v8
	s_movk_i32 s0, 0x7fc
	v_ashrrev_i32_e32 v9, 31, v8
	s_add_u32 s6, s38, 0x1802b400
	v_mov_b32_e32 v194, v30
	v_bfe_u32 v110, v30, 6, 4
	v_cmp_ne_u32_e64 s[50:51], s0, v80
	v_lshlrev_b32_e32 v82, 7, v80
	v_lshlrev_b64 v[32:33], 9, v[8:9]
	v_lshlrev_b64 v[30:31], 1, v[30:31]
	s_movk_i32 s0, 0x3800
	s_addc_u32 s7, s39, 0
	v_cmp_ne_u32_e64 s[48:49], 0, v80
	v_mov_b32_e32 v83, v195
	v_or_b32_e32 v84, 0x80, v82
	v_mov_b32_e32 v85, v195
	v_or_b32_e32 v86, 0x100, v82
	v_mov_b32_e32 v87, v195
	v_or_b32_e32 v88, 0x180, v82
	v_mov_b32_e32 v89, v195
	v_lshl_add_u64 v[90:91], v[194:195], 1, v[32:33]
	v_mad_i64_i32 v[92:93], s[0:1], v8, s0, v[30:31]
	s_mov_b32 s8, -2
	s_cmpk_lg_i32 s71, 0x100
	s_cbranch_scc1 .Lpa_l0
	s_cmpk_lt_u32 s82, 0xd0
	s_cbranch_scc1 .Lpa_l0
	s_mov_b32 s8, 10
	v_add_u32_e32 v8, 0x3000, v8
	s_mov_b64 s[0:1], 0x600000
	v_lshl_add_u64 v[90:91], v[90:91], 0, s[0:1]
	s_mov_b64 s[0:1], 0xa800000
	v_lshl_add_u64 v[92:93], v[92:93], 0, s[0:1]
.Lpa_l0:
	s_branch .LBB0_549

.LBB0_548:
	s_or_b64 exec, exec, s[0:1]
	s_mov_b64 s[0:1], 0x100000
	s_add_i32 s8, s8, 2
	v_lshl_add_u64 v[90:91], v[90:91], 0, s[0:1]
	s_mov_b64 s[0:1], 0x1c00000
	v_add_u32_e32 v8, 0x800, v8
	s_cmp_lt_u32 s8, s99
	v_lshl_add_u64 v[92:93], v[92:93], 0, s[0:1]
	s_cbranch_scc0 .LBB0_628

.LBB0_628:
	s_or_b64 exec, exec, s[4:5]
	s_cmpk_lg_i32 s71, 0x100
	s_cbranch_scc1 .Lpa_done
	s_cmpk_lt_u32 s82, 0xd0
	s_cbranch_scc1 .Lpa_done
	s_and_b32 s0, s98, 3
	s_cmp_eq_u32 s0, 3
	s_cbranch_scc1 .Lpa_done
	s_add_u32 s98, s98, 1
	s_branch .Lpa_go
.Lpa_done:
	v_lshl_add_u32 v81, s82, 9, v198
	s_waitcnt lgkmcnt(0)
	s_add_u32 s82, s38, 0x402b400
	s_mov_b32 s0, 0x18000
	s_addc_u32 s83, s39, 0
	v_cmp_gt_i32_e32 vcc, s0, v81
	s_and_saveexec_b64 s[84:85], vcc
	s_cbranch_execz .LBB0_706
	s_mov_b32 s0, 0x2aaaaaab
	v_mul_hi_i32 v0, v81, s0
	v_lshrrev_b32_e32 v1, 31, v0
	v_ashrrev_i32_e32 v0, 4, v0
	s_waitcnt vmcnt(3)
	v_add_u32_e32 v8, v0, v1
	s_movk_i32 s0, 0x60
	v_mul_lo_u32 v0, v8, s0
	s_waitcnt vmcnt(2)
	v_sub_u32_e32 v9, v81, v0
	v_lshlrev_b32_e32 v86, 3, v9
	v_lshlrev_b32_e32 v0, 2, v8
	v_ashrrev_i32_e32 v87, 31, v86
	v_and_b32_e32 v1, 0x7fc, v0
	v_and_b32_e32 v107, 0xfffff800, v0
	v_lshl_add_u64 v[2:3], v[86:87], 1, s[38:39]
	s_mov_b64 s[0:1], 0x2112b400
	v_add_u32_e32 v0, 23, v9
	v_lshl_add_u64 v[88:89], v[2:3], 0, s[0:1]
	v_cmp_lt_u32_e64 s[40:41], 46, v0
	v_subrev_u32_e32 v0, 24, v9
	s_movk_i32 s0, 0x800
	v_add_u32_e32 v2, -7, v1
	v_cmp_lt_u32_e64 s[42:43], 23, v0
	v_subrev_u32_e32 v0, 48, v9
	v_cmp_gt_u32_e64 s[48:49], s0, v2
	v_add_u32_e32 v2, -6, v1
	v_cmp_lt_u32_e64 s[44:45], 23, v0
	v_add_u32_e32 v0, -8, v1
	s_movk_i32 s1, 0x1c00
	v_cmp_gt_u32_e64 s[50:51], s0, v2
	v_mov_b32_e32 v2, 0x3800
	v_mad_i32_i24 v94, v0, s1, v2
	v_add_u32_e32 v2, -5, v1
	v_cmp_gt_u32_e64 s[52:53], s0, v2
	v_mov_b32_e32 v2, 0x5400
	v_mad_i32_i24 v96, v0, s1, v2
	v_add_u32_e32 v2, -4, v1
	v_cmp_gt_u32_e64 s[54:55], s0, v2
	v_mov_b32_e32 v2, 0x7000
	v_mad_i32_i24 v98, v0, s1, v2
	v_add_u32_e32 v2, -3, v1
	v_cmp_gt_u32_e64 s[56:57], s0, v2
	v_mov_b32_e32 v2, 0x8c00
	v_mad_i32_i24 v100, v0, s1, v2
	v_add_u32_e32 v2, -2, v1
	v_cmp_gt_u32_e64 s[58:59], s0, v2
	v_mov_b32_e32 v2, 0xa800
	v_mad_i32_i24 v102, v0, s1, v2
	v_add_u32_e32 v2, -1, v1
	v_cmp_gt_u32_e64 s[46:47], s0, v0
	v_cmp_gt_u32_e64 s[60:61], s0, v2
	v_mov_b32_e32 v2, 0xc400
	s_movk_i32 s0, 0x7fc
	v_mul_i32_i24_e32 v90, 0x1c00, v0
	v_mad_i32_i24 v92, v0, s1, s1
	v_mad_i32_i24 v104, v0, s1, v2
	v_cmp_ne_u32_e64 s[62:63], s0, v1
	s_movk_i32 s0, 0x7fb
	v_max_u32_e32 v0, 8, v1
	v_min_u32_e32 v5, 0x7f7, v1
	v_cmp_gt_u32_e64 s[64:65], s0, v1
	s_movk_i32 s0, 0x7fa
	v_sub_u32_e32 v0, v5, v0
	v_cmp_gt_u32_e64 s[66:67], s0, v1
	s_movk_i32 s0, 0x7f9
	v_add_u32_e32 v0, 17, v0
	v_cmp_gt_u32_e64 s[12:13], s0, v1
	s_movk_i32 s0, 0x7f8
	v_cvt_f32_i32_e32 v0, v0
	v_cmp_gt_u32_e64 s[4:5], s0, v1
	s_movk_i32 s0, 0x7f7
	v_cmp_gt_u32_e64 s[6:7], s0, v1
	s_movk_i32 s0, 0x7f6
	v_cmp_gt_u32_e64 s[8:9], s0, v1
	s_movk_i32 s0, 0x7f5
	v_cmp_gt_u32_e64 s[10:11], s0, v1
	v_div_scale_f32 v5, s[0:1], v0, v0, 1.0
	s_waitcnt vmcnt(1)
	v_rcp_f32_e32 v6, v5
	v_or_b32_e32 v4, 1, v1
	v_or_b32_e32 v3, 2, v1
	v_or_b32_e32 v2, 3, v1
	v_fma_f32 v7, -v5, v6, 1.0
	v_fmac_f32_e32 v6, v7, v6
	v_div_scale_f32 v7, vcc, 1.0, v0, 1.0
	v_mul_f32_e32 v14, v7, v6
	v_fma_f32 v15, -v5, v14, v7
	v_fmac_f32_e32 v14, v15, v6
	v_fma_f32 v5, -v5, v14, v7
	v_div_fmas_f32 v5, v5, v6, v14
	v_div_fixup_f32 v109, v5, v0, 1.0
	v_max_u32_e32 v0, 8, v4
	v_min_u32_e32 v5, 0x7f7, v4
	v_sub_u32_e32 v0, v5, v0
	v_add_u32_e32 v0, 17, v0
	v_cvt_f32_i32_e32 v0, v0
	s_movk_i32 s2, 0x7fd
	v_mul_u32_u24_e32 v106, 0x1c00, v1
	v_mul_u32_u24_e32 v108, 0x300, v1
	v_div_scale_f32 v5, s[0:1], v0, v0, 1.0
	v_rcp_f32_e32 v6, v5
	v_mov_b32_e32 v91, v195
	v_mov_b32_e32 v93, v195
	v_mov_b32_e32 v95, v195
	v_fma_f32 v7, -v5, v6, 1.0
	v_fmac_f32_e32 v6, v7, v6
	v_div_scale_f32 v7, vcc, 1.0, v0, 1.0
	v_mul_f32_e32 v14, v7, v6
	v_fma_f32 v15, -v5, v14, v7
	v_fmac_f32_e32 v14, v15, v6
	v_fma_f32 v5, -v5, v14, v7
	v_div_fmas_f32 v5, v5, v6, v14
	v_div_fixup_f32 v116, v5, v0, 1.0
	v_max_u32_e32 v0, 8, v3
	v_min_u32_e32 v5, 0x7f7, v3
	v_sub_u32_e32 v0, v5, v0
	v_add_u32_e32 v0, 17, v0
	v_cvt_f32_i32_e32 v0, v0
	v_mov_b32_e32 v97, v195
	v_mov_b32_e32 v99, v195
	v_mov_b32_e32 v101, v195
	v_div_scale_f32 v5, s[0:1], v0, v0, 1.0
	v_rcp_f32_e32 v6, v5
	v_mov_b32_e32 v103, v195
	v_mov_b32_e32 v105, v195
	s_mov_b32 s26, 0
	v_fma_f32 v7, -v5, v6, 1.0
	v_fmac_f32_e32 v6, v7, v6
	v_div_scale_f32 v7, vcc, 1.0, v0, 1.0
	v_mul_f32_e32 v14, v7, v6
	v_fma_f32 v15, -v5, v14, v7
	v_fmac_f32_e32 v14, v15, v6
	v_fma_f32 v5, -v5, v14, v7
	v_div_fmas_f32 v5, v5, v6, v14
	v_div_fixup_f32 v117, v5, v0, 1.0
	v_max_u32_e32 v0, 8, v2
	v_min_u32_e32 v5, 0x7f7, v2
	v_sub_u32_e32 v0, v5, v0
	v_add_u32_e32 v0, 17, v0
	v_cvt_f32_i32_e32 v0, v0
	v_div_scale_f32 v5, s[0:1], v0, v0, 1.0
	v_rcp_f32_e32 v6, v5
	s_movk_i32 s0, 0x300
	v_fma_f32 v7, -v5, v6, 1.0
	v_fmac_f32_e32 v6, v7, v6
	v_div_scale_f32 v7, vcc, 1.0, v0, 1.0
	v_mul_f32_e32 v14, v7, v6
	v_fma_f32 v15, -v5, v14, v7
	v_fmac_f32_e32 v14, v15, v6
	v_fma_f32 v5, -v5, v14, v7
	v_div_fmas_f32 v5, v5, v6, v14
	v_div_fixup_f32 v118, v5, v0, 1.0
	v_max_u32_e32 v5, 4, v1
	v_min_u32_e32 v6, 0x7fb, v1
	v_sub_u32_e32 v5, v6, v5
	v_add_u32_e32 v5, 9, v5
	v_cvt_f32_i32_e32 v5, v5
	v_mov_b32_e32 v0, 0x900
	v_mad_u32_u24 v0, v1, s0, v0
	v_lshlrev_b32_e32 v110, 1, v0
	v_div_scale_f32 v6, s[0:1], v5, v5, 1.0
	v_rcp_f32_e32 v7, v6
	s_nop 0
	v_fma_f32 v14, -v6, v7, 1.0
	v_fmac_f32_e32 v7, v14, v7
	v_div_scale_f32 v14, vcc, 1.0, v5, 1.0
	v_mul_f32_e32 v15, v14, v7
	v_fma_f32 v16, -v6, v15, v14
	v_fmac_f32_e32 v15, v16, v7
	v_fma_f32 v6, -v6, v15, v14
	v_div_fmas_f32 v6, v6, v7, v15
	v_div_fixup_f32 v119, v6, v5, 1.0
	v_max_u32_e32 v5, 4, v4
	v_min_u32_e32 v6, 0x7fb, v4
	v_sub_u32_e32 v5, v6, v5
	v_add_u32_e32 v5, 9, v5
	v_cvt_f32_i32_e32 v5, v5
	v_sub_u32_e64 v4, 2, v4 clamp
	v_xor_b32_e32 v4, 5, v4
	v_cvt_f32_ubyte0_e32 v4, v4
	v_div_scale_f32 v6, s[0:1], v5, v5, 1.0
	v_rcp_f32_e32 v7, v6
	s_nop 0
	v_fma_f32 v14, -v6, v7, 1.0
	v_fmac_f32_e32 v7, v14, v7
	v_div_scale_f32 v14, vcc, 1.0, v5, 1.0
	v_mul_f32_e32 v15, v14, v7
	v_fma_f32 v16, -v6, v15, v14
	v_fmac_f32_e32 v15, v16, v7
	v_fma_f32 v6, -v6, v15, v14
	v_div_fmas_f32 v6, v6, v7, v15
	v_div_fixup_f32 v120, v6, v5, 1.0
	v_max_u32_e32 v5, 4, v3
	v_min_u32_e32 v6, 0x7fb, v3
	v_sub_u32_e32 v5, v6, v5
	v_add_u32_e32 v5, 9, v5
	v_cvt_f32_i32_e32 v5, v5
	v_sub_u32_e64 v3, v3, s2 clamp
	v_xor_b32_e32 v3, 5, v3
	v_cvt_f32_ubyte0_e32 v3, v3
	v_div_scale_f32 v6, s[0:1], v5, v5, 1.0
	v_rcp_f32_e32 v7, v6
	s_nop 0
	v_fma_f32 v14, -v6, v7, 1.0
	v_fmac_f32_e32 v7, v14, v7
	v_div_scale_f32 v14, vcc, 1.0, v5, 1.0
	v_mul_f32_e32 v15, v14, v7
	v_fma_f32 v16, -v6, v15, v14
	v_fmac_f32_e32 v15, v16, v7
	v_fma_f32 v6, -v6, v15, v14
	v_div_fmas_f32 v6, v6, v7, v15
	v_div_fixup_f32 v121, v6, v5, 1.0
	v_max_u32_e32 v5, 4, v2
	v_min_u32_e32 v6, 0x7fb, v2
	v_sub_u32_e32 v5, v6, v5
	v_add_u32_e32 v5, 9, v5
	v_cvt_f32_i32_e32 v5, v5
	v_div_scale_f32 v6, s[0:1], v5, v5, 1.0
	v_rcp_f32_e32 v7, v6
	s_nop 0
	v_fma_f32 v14, -v6, v7, 1.0
	v_fmac_f32_e32 v7, v14, v7
	v_div_scale_f32 v14, vcc, 1.0, v5, 1.0
	v_mul_f32_e32 v15, v14, v7
	v_fma_f32 v16, -v6, v15, v14
	v_fmac_f32_e32 v15, v16, v7
	v_fma_f32 v6, -v6, v15, v14
	v_div_fmas_f32 v6, v6, v7, v15
	v_div_fixup_f32 v122, v6, v5, 1.0
	v_sub_u32_e64 v5, 2, v1 clamp
	v_sub_u32_e32 v5, 5, v5
	v_cvt_f32_ubyte0_e32 v5, v5
	v_div_scale_f32 v6, s[0:1], v5, v5, 1.0
	v_rcp_f32_e32 v7, v6
	v_sub_u32_e64 v1, 1, v1 clamp
	v_xor_b32_e32 v1, 3, v1
	v_cvt_f32_ubyte0_e32 v1, v1
	v_fma_f32 v14, -v6, v7, 1.0
	v_fmac_f32_e32 v7, v14, v7
	v_div_scale_f32 v14, vcc, 1.0, v5, 1.0
	v_mul_f32_e32 v15, v14, v7
	v_fma_f32 v16, -v6, v15, v14
	v_fmac_f32_e32 v15, v16, v7
	v_fma_f32 v6, -v6, v15, v14
	v_div_fmas_f32 v6, v6, v7, v15
	v_div_fixup_f32 v123, v6, v5, 1.0
	v_div_scale_f32 v5, s[0:1], v4, v4, 1.0
	v_rcp_f32_e32 v6, v5
	s_nop 0
	v_fma_f32 v7, -v5, v6, 1.0
	v_fmac_f32_e32 v6, v7, v6
	v_div_scale_f32 v7, vcc, 1.0, v4, 1.0
	v_mul_f32_e32 v14, v7, v6
	v_fma_f32 v15, -v5, v14, v7
	v_fmac_f32_e32 v14, v15, v6
	v_fma_f32 v5, -v5, v14, v7
	v_div_fmas_f32 v5, v5, v6, v14
	v_div_fixup_f32 v124, v5, v4, 1.0
	v_div_scale_f32 v4, s[0:1], v3, v3, 1.0
	v_rcp_f32_e32 v5, v4
	s_nop 0
	v_fma_f32 v6, -v4, v5, 1.0
	v_fmac_f32_e32 v5, v6, v5
	v_div_scale_f32 v6, vcc, 1.0, v3, 1.0
	v_mul_f32_e32 v7, v6, v5
	v_fma_f32 v14, -v4, v7, v6
	v_fmac_f32_e32 v7, v14, v5
	v_fma_f32 v4, -v4, v7, v6
	v_div_fmas_f32 v4, v4, v5, v7
	v_div_fixup_f32 v125, v4, v3, 1.0
	v_sub_u32_e64 v3, v2, s2 clamp
	v_sub_u32_e32 v3, 5, v3
	v_cvt_f32_ubyte0_e32 v3, v3
	v_div_scale_f32 v4, s[0:1], v3, v3, 1.0
	v_rcp_f32_e32 v5, v4
	s_nop 0
	v_fma_f32 v6, -v4, v5, 1.0
	v_fmac_f32_e32 v5, v6, v5
	v_div_scale_f32 v6, vcc, 1.0, v3, 1.0
	v_mul_f32_e32 v7, v6, v5
	v_fma_f32 v14, -v4, v7, v6
	v_fmac_f32_e32 v7, v14, v5
	v_fma_f32 v4, -v4, v7, v6
	v_div_fmas_f32 v4, v4, v5, v7
	v_div_fixup_f32 v126, v4, v3, 1.0
	v_div_scale_f32 v3, s[0:1], v1, v1, 1.0
	v_rcp_f32_e32 v4, v3
	s_movk_i32 s0, 0x7fe
	v_fma_f32 v5, -v3, v4, 1.0
	v_fmac_f32_e32 v4, v5, v4
	v_div_scale_f32 v5, vcc, 1.0, v1, 1.0
	v_mul_f32_e32 v6, v5, v4
	v_fma_f32 v7, -v3, v6, v5
	v_fmac_f32_e32 v6, v7, v4
	v_fma_f32 v3, -v3, v6, v5
	v_div_fmas_f32 v3, v3, v4, v6
	v_div_fixup_f32 v127, v3, v1, 1.0
	v_sub_u32_e64 v1, v2, s0 clamp
	v_xor_b32_e32 v1, 3, v1
	v_cvt_f32_ubyte0_e32 v1, v1
	v_div_scale_f32 v2, s[0:1], v1, v1, 1.0
	v_rcp_f32_e32 v3, v2
	s_nop 0
	v_fma_f32 v4, -v2, v3, 1.0
	v_fmac_f32_e32 v3, v4, v3
	v_div_scale_f32 v4, vcc, 1.0, v1, 1.0
	v_mul_f32_e32 v5, v4, v3
	v_fma_f32 v6, -v2, v5, v4
	v_fmac_f32_e32 v5, v6, v3
	v_fma_f32 v2, -v2, v5, v4
	v_div_fmas_f32 v2, v2, v3, v5
	v_div_fixup_f32 v128, v2, v1, 1.0
	s_branch .LBB0_632
